# v50 + attn_prompt: K/V block prefetch no longer waited for before the tile's QK^T (hipcc merged-path vmcnt waits removed; Q fragments are already complete)
# baseline (speedup 1.0000x reference)
; #define LAS __attribute__((address_space(3)))
; __device__ __forceinline__ void attn_prompt(const Frame& F, const bf16* QKV, bf16* OG, float* LSE) {
;     ...
;                 const int tq = (128 * n + 16 * w + fr) * dil + p;
;                 const int hp = 128 - half;
;                 f32x4 S[10];
; #pragma unroll
;                 for (int kb = 0; kb < 9; ++kb) { const int j = 16 * w + 16 * kb + fr; const int rowk = (j < 128 ? hp : half - 128) + j;
;                     const LAS unsigned char* kp = Kl + rowk * 256; f32x4 acc = {0.f, 0.f, 0.f, 0.f};
; #pragma unroll
;                     for (int ks = 0; ks < 4; ++ks) { const bf16x8 ak = *(const LAS bf16x8*)(kp + (((4 * ks + fq) ^ fr) << 4)); acc = __builtin_amdgcn_mfma_f32_16x16x32_bf16(ak, bq[ks], acc, 0, 0, 0); }
;                     S[kb] = acc; }
.LBB0_1176:
	s_add_i32 s14, s18, s49
	v_add_u32_e32 v2, s14, v89
	s_sub_i32 s14, 0x80, s15
	s_addk_i32 s15, 0xff80
	v_or_b32_e32 v3, s18, v89
	v_cmp_gt_i32_e32 vcc, s33, v3
	v_mov_b32_e32 v92, s15
	v_mov_b32_e32 v93, s14
	v_cndmask_b32_e32 v52, v92, v93, vcc
	v_xor_b32_e32 v0, v88, v89
	v_add_u32_e32 v3, v52, v3
	v_lshlrev_b32_e32 v0, 4, v0
	v_lshl_add_u32 v3, v3, 8, 0
	v_add_u32_e32 v52, v3, v0
	ds_read_b128 v[52:55], v52
	v_add_u32_e32 v56, 4, v88
	v_xor_b32_e32 v56, v56, v89
	v_lshlrev_b32_e32 v94, 4, v56
	v_add_u32_e32 v56, v3, v94
	ds_read_b128 v[56:59], v56
	s_waitcnt lgkmcnt(1)
	v_mfma_f32_16x16x32_bf16 v[52:55], v[52:55], v[4:7], 0
	s_waitcnt lgkmcnt(0)
	v_mfma_f32_16x16x32_bf16 v[52:55], v[56:59], v[8:11], v[52:55]
	v_add_u32_e32 v56, 8, v88
	v_xor_b32_e32 v56, v56, v89
	v_lshlrev_b32_e32 v96, 4, v56
	v_add_u32_e32 v56, v3, v96
	ds_read_b128 v[56:59], v56
	s_waitcnt lgkmcnt(0)
	v_mfma_f32_16x16x32_bf16 v[52:55], v[56:59], v[12:15], v[52:55]
	v_add_u32_e32 v56, 12, v88
	v_xor_b32_e32 v56, v56, v89
	v_lshlrev_b32_e32 v97, 4, v56
	v_add_u32_e32 v3, v3, v97
	ds_read_b128 v[56:59], v3
	v_or_b32_e32 v3, s20, v89
	v_cmp_gt_i32_e32 vcc, s33, v3
	s_waitcnt lgkmcnt(0)
	v_mfma_f32_16x16x32_bf16 v[84:87], v[56:59], v[16:19], v[52:55]
	s_nop 2
	v_cndmask_b32_e32 v52, v92, v93, vcc
	v_add_u32_e32 v3, v52, v3
	v_lshl_add_u32 v3, v3, 8, 0
	v_add_u32_e32 v52, v3, v0
	ds_read_b128 v[52:55], v52
	v_add_u32_e32 v56, v3, v94
	ds_read_b128 v[56:59], v56
	s_waitcnt lgkmcnt(1)
	v_mfma_f32_16x16x32_bf16 v[52:55], v[52:55], v[4:7], 0
	s_waitcnt lgkmcnt(0)
	v_mfma_f32_16x16x32_bf16 v[52:55], v[56:59], v[8:11], v[52:55]
	v_add_u32_e32 v56, v3, v96
	ds_read_b128 v[56:59], v56
	v_add_u32_e32 v3, v3, v97
	s_waitcnt lgkmcnt(0)
	v_mfma_f32_16x16x32_bf16 v[52:55], v[56:59], v[12:15], v[52:55]
	ds_read_b128 v[56:59], v3
	v_or_b32_e32 v3, s34, v89
	v_cmp_gt_i32_e32 vcc, s33, v3
	s_waitcnt lgkmcnt(0)
	v_mfma_f32_16x16x32_bf16 v[80:83], v[56:59], v[16:19], v[52:55]
	s_nop 2
	v_cndmask_b32_e32 v52, v92, v93, vcc
	v_add_u32_e32 v3, v52, v3
	v_lshl_add_u32 v3, v3, 8, 0
	v_add_u32_e32 v52, v3, v0
	ds_read_b128 v[52:55], v52
	v_add_u32_e32 v56, v3, v94
	ds_read_b128 v[56:59], v56
	s_waitcnt lgkmcnt(1)
	v_mfma_f32_16x16x32_bf16 v[52:55], v[52:55], v[4:7], 0
	s_waitcnt lgkmcnt(0)
	v_mfma_f32_16x16x32_bf16 v[52:55], v[56:59], v[8:11], v[52:55]
	v_add_u32_e32 v56, v3, v96
	ds_read_b128 v[56:59], v56
	v_add_u32_e32 v3, v3, v97
	s_waitcnt lgkmcnt(0)
	v_mfma_f32_16x16x32_bf16 v[52:55], v[56:59], v[12:15], v[52:55]
	ds_read_b128 v[56:59], v3
	v_or_b32_e32 v3, s35, v89
	v_cmp_gt_i32_e32 vcc, s33, v3
	s_waitcnt lgkmcnt(0)
	v_mfma_f32_16x16x32_bf16 v[76:79], v[56:59], v[16:19], v[52:55]
	s_nop 2
	v_cndmask_b32_e32 v52, v92, v93, vcc
	v_add_u32_e32 v3, v52, v3
	v_lshl_add_u32 v3, v3, 8, 0
	v_add_u32_e32 v52, v3, v0
	ds_read_b128 v[52:55], v52
	v_add_u32_e32 v56, v3, v94
	ds_read_b128 v[56:59], v56
	s_waitcnt lgkmcnt(1)
	v_mfma_f32_16x16x32_bf16 v[52:55], v[52:55], v[4:7], 0
	s_waitcnt lgkmcnt(0)
	v_mfma_f32_16x16x32_bf16 v[52:55], v[56:59], v[8:11], v[52:55]
	v_add_u32_e32 v56, v3, v96
	ds_read_b128 v[56:59], v56
	v_add_u32_e32 v3, v3, v97
	s_waitcnt lgkmcnt(0)
	v_mfma_f32_16x16x32_bf16 v[52:55], v[56:59], v[12:15], v[52:55]
	ds_read_b128 v[56:59], v3
	v_or_b32_e32 v3, s40, v89
	v_cmp_gt_i32_e32 vcc, s33, v3
	s_waitcnt lgkmcnt(0)
	v_mfma_f32_16x16x32_bf16 v[72:75], v[56:59], v[16:19], v[52:55]
	s_nop 2
	v_cndmask_b32_e32 v52, v92, v93, vcc
	v_add_u32_e32 v3, v52, v3
	v_lshl_add_u32 v3, v3, 8, 0
	v_add_u32_e32 v52, v3, v0
	ds_read_b128 v[52:55], v52
	v_add_u32_e32 v56, v3, v94
	ds_read_b128 v[56:59], v56
	s_waitcnt lgkmcnt(1)
	v_mfma_f32_16x16x32_bf16 v[52:55], v[52:55], v[4:7], 0
	s_waitcnt lgkmcnt(0)
	v_mfma_f32_16x16x32_bf16 v[52:55], v[56:59], v[8:11], v[52:55]
	v_add_u32_e32 v56, v3, v96
	ds_read_b128 v[56:59], v56
	v_add_u32_e32 v3, v3, v97
	s_waitcnt lgkmcnt(0)
	v_mfma_f32_16x16x32_bf16 v[52:55], v[56:59], v[12:15], v[52:55]
	ds_read_b128 v[56:59], v3
	v_or_b32_e32 v3, s41, v89
	v_cmp_gt_i32_e32 vcc, s33, v3
	s_waitcnt lgkmcnt(0)
	v_mfma_f32_16x16x32_bf16 v[68:71], v[56:59], v[16:19], v[52:55]
	s_nop 2
	v_cndmask_b32_e32 v52, v92, v93, vcc
	v_add_u32_e32 v3, v52, v3
	v_lshl_add_u32 v3, v3, 8, 0
	v_add_u32_e32 v52, v3, v0
	ds_read_b128 v[52:55], v52
	v_add_u32_e32 v56, v3, v94
	ds_read_b128 v[56:59], v56
	s_waitcnt lgkmcnt(1)
	v_mfma_f32_16x16x32_bf16 v[52:55], v[52:55], v[4:7], 0
	s_waitcnt lgkmcnt(0)
	v_mfma_f32_16x16x32_bf16 v[52:55], v[56:59], v[8:11], v[52:55]
	v_add_u32_e32 v56, v3, v96
	ds_read_b128 v[56:59], v56
	v_add_u32_e32 v3, v3, v97
	s_waitcnt lgkmcnt(0)
	v_mfma_f32_16x16x32_bf16 v[52:55], v[56:59], v[12:15], v[52:55]
	ds_read_b128 v[56:59], v3
	v_or_b32_e32 v3, s42, v89
	v_cmp_gt_i32_e32 vcc, s33, v3
	s_waitcnt lgkmcnt(0)
	v_mfma_f32_16x16x32_bf16 v[64:67], v[56:59], v[16:19], v[52:55]
	s_nop 2
	v_cndmask_b32_e32 v52, v92, v93, vcc
	v_add_u32_e32 v3, v52, v3
	v_lshl_add_u32 v3, v3, 8, 0
	v_add_u32_e32 v52, v3, v0
	ds_read_b128 v[52:55], v52
	v_add_u32_e32 v56, v3, v94
	ds_read_b128 v[56:59], v56
	s_waitcnt lgkmcnt(1)
	v_mfma_f32_16x16x32_bf16 v[52:55], v[52:55], v[4:7], 0
	s_waitcnt lgkmcnt(0)
	v_mfma_f32_16x16x32_bf16 v[52:55], v[56:59], v[8:11], v[52:55]
	v_add_u32_e32 v56, v3, v96
	ds_read_b128 v[56:59], v56
	v_add_u32_e32 v3, v3, v97
	s_waitcnt lgkmcnt(0)
	v_mfma_f32_16x16x32_bf16 v[52:55], v[56:59], v[12:15], v[52:55]
	ds_read_b128 v[56:59], v3
	v_or_b32_e32 v3, s43, v89
	v_cmp_gt_i32_e32 vcc, s33, v3
	s_waitcnt lgkmcnt(0)
	v_mfma_f32_16x16x32_bf16 v[60:63], v[56:59], v[16:19], v[52:55]
	s_nop 2
	v_cndmask_b32_e32 v52, v92, v93, vcc
	v_add_u32_e32 v3, v52, v3
	v_lshl_add_u32 v3, v3, 8, 0
	v_add_u32_e32 v52, v3, v0
	ds_read_b128 v[52:55], v52
	v_add_u32_e32 v56, v3, v94
	ds_read_b128 v[56:59], v56
	s_waitcnt lgkmcnt(1)
	v_mfma_f32_16x16x32_bf16 v[52:55], v[52:55], v[4:7], 0
	s_waitcnt lgkmcnt(0)
	v_mfma_f32_16x16x32_bf16 v[52:55], v[56:59], v[8:11], v[52:55]
	v_add_u32_e32 v56, v3, v96
	ds_read_b128 v[56:59], v56
	v_add_u32_e32 v3, v3, v97
	s_waitcnt lgkmcnt(0)
	v_mfma_f32_16x16x32_bf16 v[52:55], v[56:59], v[12:15], v[52:55]
	ds_read_b128 v[56:59], v3
	v_or_b32_e32 v3, s19, v89
	v_cmp_gt_i32_e32 vcc, s33, v3
	s_waitcnt lgkmcnt(0)
	v_mfma_f32_16x16x32_bf16 v[56:59], v[56:59], v[16:19], v[52:55]
	s_nop 2
	v_cndmask_b32_e32 v52, v92, v93, vcc
	v_add_u32_e32 v3, v52, v3
	v_lshl_add_u32 v3, v3, 8, 0
	v_add_u32_e32 v0, v3, v0
	ds_read_b128 v[52:55], v0
	v_add_u32_e32 v0, v3, v94
	ds_read_b128 v[92:95], v0
	s_waitcnt lgkmcnt(1)
	v_mfma_f32_16x16x32_bf16 v[52:55], v[52:55], v[4:7], 0
	v_add_u32_e32 v0, v3, v96
	s_andn2_b64 vcc, exec, s[10:11]
	s_waitcnt lgkmcnt(0)
	v_mfma_f32_16x16x32_bf16 v[52:55], v[92:95], v[8:11], v[52:55]
	ds_read_b128 v[92:95], v0
	v_add_u32_e32 v0, v3, v97
	s_waitcnt lgkmcnt(0)
	v_mfma_f32_16x16x32_bf16 v[52:55], v[92:95], v[12:15], v[52:55]
	ds_read_b128 v[92:95], v0
	s_waitcnt lgkmcnt(0)
	v_mfma_f32_16x16x32_bf16 v[52:55], v[92:95], v[16:19], v[52:55]
	s_cbranch_vccnz .LBB0_1178
; #define ATT_PREFETCH_Q(qbase_, blk_) do { const bf16* qb_ = (qbase_) + (size_t)((blk_) * 128 + 16 * w + fr) * 128 + 8 * fq; \
;         _Pragma("unroll") for (int ks = 0; ks < 4; ++ks) bq[ks] = *(const bf16x8*)(qb_ + 32 * ks); } while (0)
; __device__ __forceinline__ void attn_prompt(const Frame& F, const bf16* QKV, bf16* OG, float* LSE) {
;     ...
;                 if (s + 1 < nt) ATT_PREFETCH_Q(qbase, n + 1);
	v_ashrrev_i32_e32 v3, 31, v2
	v_lshlrev_b64 v[4:5], 8, v[2:3]
	v_lshlrev_b32_e32 v6, 3, v88
	v_lshl_add_u64 v[4:5], s[24:25], 0, v[4:5]
	v_ashrrev_i32_e32 v7, 31, v6
	v_lshl_add_u64 v[16:17], v[6:7], 1, v[4:5]
	global_load_dwordx4 v[4:7], v[16:17], off
	global_load_dwordx4 v[8:11], v[16:17], off offset:64
	global_load_dwordx4 v[12:15], v[16:17], off offset:128
	s_nop 0
	global_load_dwordx4 v[16:19], v[16:17], off offset:192

; #define ATT_PREFETCH_BLK(kbase_, blk_) do { const bf16* ks_ = (kbase_) + (size_t)((blk_) * 128 + kq) * 128 + ch * 8; \
;         _Pragma("unroll") for (int i = 0; i < 4; ++i) { kraw[i] = *(const v4u*)(ks_ + (size_t)i * 32 * 128); vraw[i] = *(const v4u*)(ks_ + (size_t)i * 32 * 128 + (size_t)8 * 2 * 4096 * 128); } } while (0)
; #define ATT_PREFETCH_Q(qbase_, blk_) do { const bf16* qb_ = (qbase_) + (size_t)((blk_) * 128 + 16 * w + fr) * 128 + 8 * fq; \
;         _Pragma("unroll") for (int ks = 0; ks < 4; ++ks) bq[ks] = *(const bf16x8*)(qb_ + 32 * ks); } while (0)
; __device__ __forceinline__ void attn_prompt(const Frame& F, const bf16* QKV, bf16* OG, float* LSE) {
;     ...
;             if (s + 1 < nt) { ATT_PREFETCH_BLK(kbase, n + 1); if (s < 0) ATT_PREFETCH_Q(qbase, n + 1); }
;             if (s >= 0) {
.LBB0_1183:
	s_add_i32 s14, s18, s49
	v_add_u32_e32 v2, s14, v89
	v_ashrrev_i32_e32 v3, 31, v2
	v_lshlrev_b64 v[2:3], 8, v[2:3]
	v_lshlrev_b32_e32 v4, 3, v88
	v_lshl_add_u64 v[2:3], s[24:25], 0, v[2:3]
	v_ashrrev_i32_e32 v5, 31, v4
	v_lshl_add_u64 v[2:3], v[4:5], 1, v[2:3]
	global_load_dwordx4 v[4:7], v[2:3], off
	global_load_dwordx4 v[8:11], v[2:3], off offset:64
	global_load_dwordx4 v[12:15], v[2:3], off offset:128
	global_load_dwordx4 v[16:19], v[2:3], off offset:192
	s_cmp_lt_i32 s38, 0
	s_cbranch_scc1 .LBB0_1181
	s_waitcnt vmcnt(0)
	s_branch .LBB0_1176
